# attention: all waves un-shifted, softmax exp/rowsum VALU interleaved into the MFMA stream
# speedup vs baseline: 1.0034x; 1.0034x over previous
; #define LAS __attribute__((address_space(3)))
; DI int opaque_tid() { int t = threadIdx.x; asm volatile("" : "+v"(t)); return t; }
; #define AT_ISSUE_K(tile, slot) do { const char* g_ = kbu + (size_t)(tile) * (64 * D * 2) + kso; AT_DMA(g_, KRING + (slot) * SLOT + wid * 1024); AT_DMA(g_ + 128, KRING + (slot) * SLOT + 8192 + wid * 1024); } while (0)
; DI void attn_unit(const bf16_t* Q, const bf16_t* Kp, const bf16_t* Vp, bf16_t* O, size_t qrow0, size_t krow0, int ntile, int h, float lam, float lam_init, const float* gsub, LAS unsigned char* lds) {
;     const int tid = opaque_tid(), lane = tid & 63, wid = __builtin_amdgcn_readfirstlane(tid >> 6), r32 = lane & 31, hh = lane >> 5;
;     const int sub = wid & 1, qg = wid >> 1;
;     constexpr int KRING = 0, VRING = 65536, SLOT = 16384;
;     bf16x8 qf[4];
;     { const bf16_t* qp = Q + (qrow0 + 32 * qg + r32) * D + h * 128 + sub * 64 + 8 * hh;
; #pragma unroll
;       for (int d0 = 0; d0 < 4; ++d0) qf[d0] = *(const bf16x8*)(qp + 16 * d0); }
;     f32x16 ot[4];
; #pragma unroll
;     for (int d = 0; d < 4; ++d)
; #pragma unroll
;         for (int i = 0; i < 16; ++i) ot[d][i] = 0.f;
;     float m_run = -1e30f, l_run = 0.f;
;     const char* kbu = (const char*)(Kp + krow0 * D + h * 128); const char* vbu = (const char*)(Vp + krow0 * D + h * 128);
;     unsigned kso, vso0, vso1;
;     { const int kr = 8 * wid + (lane >> 3); const int kc = (lane & 7) ^ ((kr >> 1) & 7); kso = (unsigned)((kr * D + kc * 8) * 2);
;       const int vr0 = 4 * wid + (lane >> 4), vr1 = vr0 + 32; const int vc = (lane & 15) ^ (4 * (vr0 & 3));
;       vso0 = (unsigned)((vr0 * D + vc * 8) * 2); vso1 = (unsigned)((vr1 * D + vc * 8) * 2); }
;     const unsigned ldsb = (unsigned)(unsigned long)lds;
;     ...
;     asm volatile("s_waitcnt lgkmcnt(0)" ::: "memory"); __builtin_amdgcn_s_barrier();
;     AT_ISSUE_K(0, 0); AT_ISSUE_K(1, 1); AT_ISSUE_K(2, 2); AT_ISSUE_K(3, 3); AT_ISSUE_V(0, 0); AT_ISSUE_V(1, 1);
;     { const u32x4 z = {0u, 0u, 0u, 0u}; *(LAS u32x4*)(lds + VRING + 3 * SLOT + tid * 16) = z; *(LAS u32x4*)(lds + VRING + 3 * SLOT + 8192 + tid * 16) = z; }
;     asm volatile("s_waitcnt vmcnt(0) lgkmcnt(0)" ::: "memory"); __builtin_amdgcn_s_barrier(); asm volatile("" ::: "memory");
.LBB0_567:
	s_and_b64 vcc, exec, s[40:41]
	s_cbranch_vccz .LBB0_570
	s_ashr_i32 s54, s56, 8
	s_lshl_b32 s46, s56, 7
	s_mul_i32 s41, s54, 0x1100
	s_and_b32 s46, s46, 0xf80
	s_mul_hi_i32 s40, s54, 0x1100
	s_add_u32 s46, s41, s46
	s_addc_u32 s47, s40, 0
	v_readlane_b32 s40, v253, 57
	v_cmp_lt_u64_e32 vcc, s[46:47], v[238:239]
	v_readlane_b32 s41, v253, 58
	s_and_b64 s[40:41], s[40:41], vcc
	s_and_b64 s[40:41], s[40:41], exec
	v_mov_b32_e32 v1, v206
	s_cselect_b32 s51, s65, s59
	v_readfirstlane_b32 s41, v1
	s_cselect_b32 s50, s64, s58
	s_ashr_i32 s67, s41, 7
	v_and_b32_e32 v6, 31, v1
	s_lshl_b32 s52, s67, 5
	s_ashr_i32 s53, s52, 31
	v_or_b32_e32 v2, s46, v6
	v_mov_b32_e32 v3, s47
	s_ashr_i32 s40, s41, 6
	v_lshl_add_u64 v[34:35], v[2:3], 0, s[52:53]
	s_lshl_b32 s41, s56, 2
	v_lshlrev_b64 v[2:3], 11, v[34:35]
	s_and_b32 s46, s41, 0x380
	s_and_b32 s66, s40, 1
	v_lshl_add_u64 v[2:3], s[50:51], 0, v[2:3]
	s_lshl_b32 s92, s46, 1
	v_bfe_u32 v37, v1, 5, 1
	v_lshl_add_u64 v[2:3], v[2:3], 0, s[92:93]
	s_lshl_b32 s50, s66, 7
	s_mov_b32 s51, s93
	v_lshl_add_u64 v[2:3], v[2:3], 0, s[50:51]
	v_lshlrev_b32_e32 v4, 4, v37
	v_mov_b32_e32 v5, v0
	v_lshl_add_u64 v[2:3], v[2:3], 0, v[4:5]
	flat_load_dwordx4 v[146:149], v[2:3]
	flat_load_dwordx4 v[150:153], v[2:3] offset:32
	flat_load_dwordx4 v[154:157], v[2:3] offset:64
	flat_load_dwordx4 v[158:161], v[2:3] offset:96
	s_mul_hi_i32 s41, s54, 0x880000
	s_mul_i32 s54, s54, 0x880000
	s_add_u32 s47, s60, s54
	s_addc_u32 s50, s61, s41
	s_add_u32 s52, s47, s92
	s_addc_u32 s53, s50, 0
	v_bfe_u32 v2, v1, 3, 3
	s_add_u32 s47, s62, s54
	v_lshl_or_b32 v2, s40, 3, v2
	s_addc_u32 s41, s63, s41
	v_lshrrev_b32_e32 v3, 1, v2
	s_add_u32 s50, s47, s92
	v_xor_b32_e32 v3, v3, v1
	v_bfe_u32 v39, v1, 4, 2
	v_and_b32_e32 v38, 15, v1
	s_addc_u32 s51, s41, 0
	v_lshlrev_b32_e32 v2, 11, v2
	v_lshlrev_b32_e32 v3, 4, v3
	s_movk_i32 s41, 0x70
	v_lshlrev_b32_e32 v4, 6, v39
	v_lshlrev_b32_e32 v5, 4, v38
	v_and_or_b32 v2, v3, s41, v2
	v_lshlrev_b32_e32 v3, 11, v39
	s_lshl_b32 s41, s40, 13
	v_xor_b32_e32 v4, v5, v4
	v_or3_b32 v194, s41, v3, v4
	v_mov_b32_e32 v3, v0
	s_lshl_b32 s68, s40, 10
	s_waitcnt lgkmcnt(0)
	s_barrier
	v_lshl_add_u64 v[198:199], s[52:53], 0, v[2:3]
	s_add_i32 s41, s68, 0
	s_mov_b32 s47, m0
	s_mov_b32 m0, s41
	s_nop 0
	global_load_lds_dwordx4 v[198:199], off
	s_mov_b32 m0, s47
	s_add_i32 s47, s41, 0x2000
	v_lshl_add_u64 v[2:3], v[198:199], 0, s[90:91]
	s_mov_b32 s52, m0
	s_mov_b32 m0, s47
	s_nop 0
	global_load_lds_dwordx4 v[2:3], off
	s_mov_b32 m0, s52
	s_mov_b64 s[52:53], 0x20000
	v_lshl_add_u64 v[2:3], v[198:199], 0, s[52:53]
	s_add_i32 s47, s41, 0x4000
	s_mov_b32 s52, m0
	s_mov_b32 m0, s47
	s_nop 0
	global_load_lds_dwordx4 v[2:3], off
	s_mov_b32 m0, s52
	s_mov_b64 s[52:53], 0x20080
	s_add_i32 s47, s41, 0x6000
	v_lshl_add_u64 v[2:3], v[198:199], 0, s[52:53]
	s_mov_b32 s52, m0
	s_mov_b32 m0, s47
	s_nop 0
	global_load_lds_dwordx4 v[2:3], off
	s_mov_b32 m0, s52
	s_mov_b64 s[52:53], 0x40000
	v_lshl_add_u64 v[2:3], v[198:199], 0, s[52:53]
	s_add_i32 s47, s41, 0x8000
	s_mov_b32 s52, m0
	s_mov_b32 m0, s47
	s_nop 0
	global_load_lds_dwordx4 v[2:3], off
	s_mov_b32 m0, s52
	s_mov_b64 s[52:53], 0x40080
	s_add_i32 s47, s41, 0xa000
	v_lshl_add_u64 v[2:3], v[198:199], 0, s[52:53]
	s_mov_b32 s52, m0
	s_mov_b32 m0, s47
	s_nop 0
	global_load_lds_dwordx4 v[2:3], off
	s_mov_b32 m0, s52
	s_mov_b64 s[52:53], 0x60000
	v_lshl_add_u64 v[2:3], v[198:199], 0, s[52:53]
	s_add_i32 s47, s41, 0xc000
	s_mov_b32 s52, m0
	s_mov_b32 m0, s47
	s_nop 0
	global_load_lds_dwordx4 v[2:3], off
	s_mov_b32 m0, s52
	s_mov_b64 s[52:53], 0x60080
	s_add_i32 s47, s41, 0xe000
	v_lshl_add_u64 v[2:3], v[198:199], 0, s[52:53]
	s_mov_b32 s52, m0
	s_mov_b32 m0, s47
	s_nop 0
	global_load_lds_dwordx4 v[2:3], off
	s_mov_b32 m0, s52
	v_mov_b32_e32 v195, v0
	v_add_u32_e32 v196, 0x10000, v194
	s_add_i32 s47, s41, 0x10000
	v_lshl_add_u64 v[2:3], s[50:51], 0, v[194:195]
	s_mov_b32 s52, m0
	s_mov_b32 m0, s47
	s_nop 0
	global_load_lds_dwordx4 v[2:3], off
	s_mov_b32 m0, s52
	v_mov_b32_e32 v197, v0
	s_add_i32 s47, s41, 0x12000
	v_lshl_add_u64 v[2:3], s[50:51], 0, v[196:197]
	s_mov_b32 s52, m0
	s_mov_b32 m0, s47
	s_nop 0
	global_load_lds_dwordx4 v[2:3], off
	s_mov_b32 m0, s52
	s_add_u32 s52, s50, 0x20000
	s_addc_u32 s53, s51, 0
	v_lshl_add_u64 v[2:3], s[52:53], 0, v[194:195]
	s_add_i32 s47, s41, 0x14000
	s_mov_b32 s54, m0
	s_mov_b32 m0, s47
	s_nop 0
	global_load_lds_dwordx4 v[2:3], off
	s_mov_b32 m0, s54
	v_lshl_add_u64 v[2:3], s[52:53], 0, v[196:197]
	s_mov_b32 s92, s93
	s_add_i32 s41, s41, 0x16000
	s_mov_b32 s47, m0
	s_mov_b32 m0, s41
	s_nop 0
	global_load_lds_dwordx4 v[2:3], off
	s_mov_b32 m0, s47
	v_lshl_add_u32 v2, v1, 4, 0
	s_mov_b32 s94, s93
	s_mov_b32 s95, s93
	v_mov_b64_e32 v[8:9], s[92:93]
	v_add_u32_e32 v3, 0x1c000, v2
	v_mov_b64_e32 v[10:11], s[94:95]
	v_add_u32_e32 v2, 0x1e000, v2
	ds_write_b128 v2, v[8:11]
	v_lshrrev_b32_e32 v2, 1, v1
	s_lshl_b32 s41, s66, 13
	s_add_i32 s41, s41, 0
	v_bitop3_b32 v2, v37, v2, 7 bitop3:0x78
	ds_write_b128 v3, v[8:11]
	v_lshl_add_u32 v200, v6, 7, s41
	v_lshlrev_b32_e32 v201, 4, v2
	s_waitcnt vmcnt(0) lgkmcnt(0)
	s_barrier
; #define LAS __attribute__((address_space(3)))
; #define MFMA32(a, b, c) __builtin_amdgcn_mfma_f32_32x32x16_bf16((a), (b), (c), 0, 0, 0)
; DI void attn_unit(const bf16_t* Q, const bf16_t* Kp, const bf16_t* Vp, bf16_t* O, size_t qrow0, size_t krow0, int ntile, int h, float lam, float lam_init, const float* gsub, LAS unsigned char* lds) {
;     ...
;     const int q4 = (lane & 15) >> 2, p4 = lane & 3, blk = (lane >> 4) & 1;
;     const int ksw = (r32 >> 1) & 7;
;     const int kro = sub * 8192 + r32 * 128;
;     const int vro = (4 * hh + q4) * 256 + blk * 32 + p4 * 8;
;     f32x16 sc[2], sn[2];
; #pragma unroll
;     for (int kh = 0; kh < 2; ++kh) {
; #pragma unroll
;         for (int i = 0; i < 16; ++i) sc[kh][i] = 0.f;
; #pragma unroll
;         for (int d0 = 0; d0 < 4; ++d0) { const bf16x8 kf = *(const LAS bf16x8*)(lds + KRING + kro + kh * 4096 + (((2 * d0 + hh) ^ ksw) * 16)); sc[kh] = MFMA32(kf, qf[d0], sc[kh]); }
;     }
;     u32x4 pp[4];
; #pragma unroll
;     for (int j = 0; j < 4; ++j) pp[j] = (u32x4){0u, 0u, 0u, 0u};
;     constexpr float AT_TRIG = 16384.f;
;     f32x16 negm;
;     { float mx = fmaxf(fmaxf(sc[0][0], sc[0][1]), sc[0][2]);
; #pragma unroll
;       for (int i = 3; i < 15; i += 2) mx = fmaxf(fmaxf(mx, sc[0][i]), sc[0][i + 1]);
;       mx = fmaxf(mx, sc[0][15]);
; #pragma unroll
;       for (int i = 0; i < 16; i += 2) mx = fmaxf(fmaxf(mx, sc[1][i]), sc[1][i + 1]);
;       mx = fmaxf(mx, __shfl_xor(mx, 32));
; #pragma unroll
;       for (int i = 0; i < 16; ++i) { negm[i] = -mx; sc[0][i] -= mx; sc[1][i] -= mx; } }
;     asm volatile("s_waitcnt lgkmcnt(0)" ::: "memory"); __builtin_amdgcn_s_barrier(); asm volatile("" ::: "memory");
;     const bool shifted = wid >= 4;
;     float ps = 0.f;
;     if (shifted) {
; #pragma unroll
;         for (int kh = 0; kh < 2; ++kh)
; #pragma unroll
;             for (int i = 0; i < 16; ++i) { sc[kh][i] = __builtin_amdgcn_exp2f(sc[kh][i]); ps += sc[kh][i]; }
;         l_run += ps;
;     }
	v_add_u32_e32 v23, v200, v201
	ds_read_b128 v[2:5], v23
	v_bfe_u32 v22, v1, 1, 3
	v_bitop3_b32 v18, v37, v22, 2 bitop3:0x36
	v_lshlrev_b32_e32 v202, 4, v18
	v_add_u32_e32 v36, v200, v202
	ds_read_b128 v[18:21], v36
	s_waitcnt vmcnt(0) lgkmcnt(0)
	v_mfma_f32_32x32x16_bf16 v[2:17], v[2:5], v[146:149], 0
	ds_read_b128 v[40:43], v36 offset:4096
	s_mov_b64 s[52:53], 0
	s_mov_b64 s[54:55], -1
	s_mov_b32 s77, 0
	v_mfma_f32_32x32x16_bf16 v[2:17], v[18:21], v[150:153], v[2:17]
	v_bitop3_b32 v18, v37, v22, 4 bitop3:0x36
	v_lshlrev_b32_e32 v203, 4, v18
	v_add_u32_e32 v44, v200, v203
	ds_read_b128 v[18:21], v44
	s_waitcnt lgkmcnt(0)
	v_mfma_f32_32x32x16_bf16 v[2:17], v[18:21], v[154:157], v[2:17]
	v_bitop3_b32 v18, v37, v22, 6 bitop3:0x36
	v_lshlrev_b32_e32 v204, 4, v18
	v_add_u32_e32 v45, v200, v204
	ds_read_b128 v[18:21], v45
	s_waitcnt lgkmcnt(0)
	v_mfma_f32_32x32x16_bf16 v[2:17], v[18:21], v[158:161], v[2:17]
	ds_read_b128 v[18:21], v23 offset:4096
	s_nop 10
	v_max_f32_e32 v36, v3, v3
	s_waitcnt lgkmcnt(0)
	v_mfma_f32_32x32x16_bf16 v[18:33], v[18:21], v[146:149], 0
	v_mfma_f32_32x32x16_bf16 v[18:33], v[40:43], v[150:153], v[18:33]
	ds_read_b128 v[40:43], v44 offset:4096
	s_waitcnt lgkmcnt(0)
	v_mfma_f32_32x32x16_bf16 v[18:33], v[40:43], v[154:157], v[18:33]
	ds_read_b128 v[40:43], v45 offset:4096
	s_waitcnt lgkmcnt(0)
	s_barrier
	s_waitcnt lgkmcnt(0)
	v_mfma_f32_32x32x16_bf16 v[18:33], v[40:43], v[158:161], v[18:33]
	v_max_f32_e32 v40, v2, v2
	v_max_f32_e32 v36, v40, v36
	v_max3_f32 v36, v36, v4, v5
	v_max3_f32 v36, v36, v6, v7
	v_max3_f32 v36, v36, v8, v9
	v_max3_f32 v36, v36, v10, v11
	v_max3_f32 v36, v36, v12, v13
	v_max3_f32 v36, v36, v14, v15
	v_max3_f32 v36, v36, v16, v17
	s_nop 2
	v_max3_f32 v36, v36, v18, v19
	v_max3_f32 v36, v36, v20, v21
	v_max3_f32 v36, v36, v22, v23
	v_max3_f32 v36, v36, v24, v25
	v_and_b32_e32 v41, 64, v209
	v_max3_f32 v36, v36, v26, v27
	v_xor_b32_e32 v40, 32, v209
	v_add_u32_e32 v41, 64, v41
	v_max3_f32 v36, v36, v28, v29
	v_cmp_lt_i32_e32 vcc, v40, v41
	v_max3_f32 v36, v36, v30, v31
	v_max3_f32 v36, v36, v32, v33
	v_cndmask_b32_e32 v40, v209, v40, vcc
	v_lshlrev_b32_e32 v191, 2, v40
	ds_bpermute_b32 v40, v191, v36
	s_and_b64 vcc, exec, s[54:55]
	s_waitcnt lgkmcnt(0)
	v_max_f32_e32 v40, v40, v40
	v_max_f32_e32 v36, v36, v40
	v_pk_add_f32 v[66:67], v[2:3], v[36:37] op_sel_hi:[1,0] neg_lo:[0,1] neg_hi:[0,1]
	v_pk_add_f32 v[82:83], v[18:19], v[36:37] op_sel_hi:[1,0] neg_lo:[0,1] neg_hi:[0,1]
	v_pk_add_f32 v[68:69], v[4:5], v[36:37] op_sel_hi:[1,0] neg_lo:[0,1] neg_hi:[0,1]
	v_pk_add_f32 v[84:85], v[20:21], v[36:37] op_sel_hi:[1,0] neg_lo:[0,1] neg_hi:[0,1]
	v_pk_add_f32 v[70:71], v[6:7], v[36:37] op_sel_hi:[1,0] neg_lo:[0,1] neg_hi:[0,1]
	v_pk_add_f32 v[86:87], v[22:23], v[36:37] op_sel_hi:[1,0] neg_lo:[0,1] neg_hi:[0,1]
	v_pk_add_f32 v[72:73], v[8:9], v[36:37] op_sel_hi:[1,0] neg_lo:[0,1] neg_hi:[0,1]
	v_pk_add_f32 v[88:89], v[24:25], v[36:37] op_sel_hi:[1,0] neg_lo:[0,1] neg_hi:[0,1]
	v_pk_add_f32 v[74:75], v[10:11], v[36:37] op_sel_hi:[1,0] neg_lo:[0,1] neg_hi:[0,1]
	v_pk_add_f32 v[90:91], v[26:27], v[36:37] op_sel_hi:[1,0] neg_lo:[0,1] neg_hi:[0,1]
	v_pk_add_f32 v[76:77], v[12:13], v[36:37] op_sel_hi:[1,0] neg_lo:[0,1] neg_hi:[0,1]
	v_pk_add_f32 v[92:93], v[28:29], v[36:37] op_sel_hi:[1,0] neg_lo:[0,1] neg_hi:[0,1]
	v_pk_add_f32 v[78:79], v[14:15], v[36:37] op_sel_hi:[1,0] neg_lo:[0,1] neg_hi:[0,1]
	v_pk_add_f32 v[94:95], v[30:31], v[36:37] op_sel_hi:[1,0] neg_lo:[0,1] neg_hi:[0,1]
	v_pk_add_f32 v[80:81], v[16:17], v[36:37] op_sel_hi:[1,0] neg_lo:[0,1] neg_hi:[0,1]
	v_pk_add_f32 v[96:97], v[32:33], v[36:37] op_sel_hi:[1,0] neg_lo:[0,1] neg_hi:[0,1]
	s_cbranch_vccnz .LBB0_571
	v_exp_f32_e32 v66, v66
	v_exp_f32_e32 v67, v67
	v_exp_f32_e32 v68, v68
	v_exp_f32_e32 v69, v69
	v_add_f32_e32 v2, 0, v66
	v_exp_f32_e32 v70, v70
	v_add_f32_e32 v2, v67, v2
	v_exp_f32_e32 v71, v71
	v_add_f32_e32 v2, v68, v2
	v_exp_f32_e32 v72, v72
	v_add_f32_e32 v2, v69, v2
	v_exp_f32_e32 v73, v73
	v_add_f32_e32 v2, v70, v2
	v_exp_f32_e32 v74, v74
	v_add_f32_e32 v2, v71, v2
	v_exp_f32_e32 v75, v75
	v_add_f32_e32 v2, v72, v2
	v_exp_f32_e32 v76, v76
	v_add_f32_e32 v2, v73, v2
	v_exp_f32_e32 v77, v77
	v_add_f32_e32 v2, v74, v2
	v_exp_f32_e32 v78, v78
	v_add_f32_e32 v2, v75, v2
	v_exp_f32_e32 v79, v79
	v_add_f32_e32 v2, v76, v2
	v_exp_f32_e32 v80, v80
	v_add_f32_e32 v2, v77, v2
	v_exp_f32_e32 v81, v81
	v_add_f32_e32 v2, v78, v2
	v_exp_f32_e32 v82, v82
	v_add_f32_e32 v2, v79, v2
	v_exp_f32_e32 v83, v83
	v_add_f32_e32 v2, v80, v2
	v_exp_f32_e32 v84, v84
	v_add_f32_e32 v2, v81, v2
	v_exp_f32_e32 v85, v85
	v_add_f32_e32 v2, v82, v2
	v_exp_f32_e32 v86, v86
	v_add_f32_e32 v2, v83, v2
	v_exp_f32_e32 v87, v87
	v_add_f32_e32 v2, v84, v2
	v_exp_f32_e32 v88, v88
	v_add_f32_e32 v2, v85, v2
	v_exp_f32_e32 v89, v89
	v_add_f32_e32 v2, v86, v2
	v_exp_f32_e32 v90, v90
	v_add_f32_e32 v2, v87, v2
	v_exp_f32_e32 v91, v91
	v_add_f32_e32 v2, v88, v2
	v_exp_f32_e32 v92, v92
	v_add_f32_e32 v2, v89, v2
	v_exp_f32_e32 v93, v93
	v_add_f32_e32 v2, v90, v2
	v_exp_f32_e32 v94, v94
	v_add_f32_e32 v2, v91, v2
	v_exp_f32_e32 v95, v95
	v_add_f32_e32 v2, v92, v2
	v_exp_f32_e32 v96, v96
	v_add_f32_e32 v2, v93, v2
	v_exp_f32_e32 v97, v97
	v_add_f32_e32 v2, v94, v2
	v_add_f32_e32 v2, v95, v2
	v_add_f32_e32 v2, v96, v2
	v_add_f32_e32 v220, v97, v2
	v_add_f32_e32 v213, 0, v220
	s_branch .LBB0_572

; #define LAS __attribute__((address_space(3)))
; #define MFMA32(a, b, c) __builtin_amdgcn_mfma_f32_32x32x16_bf16((a), (b), (c), 0, 0, 0)
; DI void attn_unit(const bf16_t* Q, const bf16_t* Kp, const bf16_t* Vp, bf16_t* O, size_t qrow0, size_t krow0, int ntile, int h, float lam, float lam_init, const float* gsub, LAS unsigned char* lds) {
;     ...
;       {
;         { const int tk = (t + 4 < ntile) ? t + 4 : ntile - 1; AT_ISSUE_K(tk, ks0); const int tv = (t + 2 < ntile) ? t + 2 : ntile - 1; AT_ISSUE_V(tv, vs1); }
;         LAS unsigned char* kb = lds + KRING + ks1 * SLOT + kro;
;         LAS unsigned char* vb = lds + VRING + vsm1 * SLOT + vro;
;         __builtin_amdgcn_s_setprio(1);
;         { bf16x8 ql[4];
; #pragma unroll
;           for (int d0 = 0; d0 < 4; ++d0) ql[d0] = qf[d0];
; #pragma unroll
;           for (int kh = 0; kh < 2; ++kh) {
;             bf16x8 kf[4];
; #pragma unroll
;             for (int e = 0; e < 4; ++e) kf[e] = *(const LAS bf16x8*)(kb + kh * 4096 + (((2 * e + hh) ^ ksw) * 16));
;             sn[kh] = MFMA32(kf[0], ql[0], negm);
; #pragma unroll
;             for (int d0 = 1; d0 < 4; ++d0) sn[kh] = MFMA32(kf[d0], ql[d0], sn[kh]);
;             __builtin_amdgcn_sched_barrier(0);
;           } }
; #pragma unroll
;         for (int j = 0; j < 4; ++j) {
;             s16x4 lo[4], hi[4];
; #pragma unroll
;             for (int e = 0; e < 4; ++e) { LAS unsigned char* vp = vb + j * 4096 + ((e ^ q4) * 64);
;                 lo[e] = __builtin_bit_cast(s16x4, __builtin_amdgcn_ds_read_tr16_b64_v4i16((LAS s16x4*)vp));
;                 hi[e] = __builtin_bit_cast(s16x4, __builtin_amdgcn_ds_read_tr16_b64_v4i16((LAS s16x4*)(vp + 2048))); }
; #pragma unroll
;             for (int e = 0; e < 4; ++e) ot[e] = MFMA32(__builtin_shufflevector(lo[e], hi[e], 0, 1, 2, 3, 4, 5, 6, 7), __builtin_bit_cast(bf16x8, pp[j]), ot[e]);
;             __builtin_amdgcn_sched_barrier(0);
;         }
;         __builtin_amdgcn_s_setprio(0);
;         if (!shifted) {
;             ps = 0.f;
; #pragma unroll
;             for (int kh = 0; kh < 2; ++kh)
; #pragma unroll
;                 for (int i = 0; i < 16; ++i) { sc[kh][i] = __builtin_amdgcn_exp2f(sc[kh][i]); ps += sc[kh][i]; }
;             l_run += ps;
;         }
.LBB0_573:
	s_min_u32 s40, s76, 63
	s_lshl_b32 s92, s40, 17
	s_lshl_b32 s80, s74, 14
	s_lshl_b32 s78, s70, 14
	s_setprio 1
	v_add_u32_e32 v1, s80, v200
	v_add_u32_e32 v226, v1, v201
	v_add_u32_e32 v207, v1, v202
	v_add_u32_e32 v221, v1, v203
	v_add_u32_e32 v1, v1, v204
	ds_read_b128 v[182:185], v226
	ds_read_b128 v[222:225], v207
	ds_read_b128 v[228:231], v221
	ds_read_b128 v[240:243], v1
	ds_read_b128 v[244:247], v226 offset:4096
	ds_read_b128 v[248:251], v207 offset:4096
	v_add_u32_e32 v227, s78, v219
	v_add_u32_e32 v226, v227, v218
	v_add_u32_e32 v207, v227, v217
	v_add_u32_e32 v235, v227, v216
	v_add_u32_e32 v227, v227, v214
	v_lshl_add_u64 v[232:233], v[198:199], 0, s[92:93]
	s_mov_b64 s[40:41], 0x80000
	v_lshl_add_u64 v[232:233], v[232:233], 0, s[40:41]
	s_lshl_b32 s40, s77, 14
	s_add_i32 s41, s40, s68
	s_mov_b32 s75, m0
	s_mov_b32 m0, s41
	s_nop 0
	global_load_lds_dwordx4 v[232:233], off
	s_mov_b32 m0, s75
	s_add_i32 s75, s40, s71
	s_mov_b64 s[40:41], 0x80
	v_lshl_add_u64 v[232:233], v[232:233], 0, s[40:41]
	s_mov_b32 s40, m0
	s_mov_b32 m0, s75
	s_nop 0
	global_load_lds_dwordx4 v[232:233], off
	s_mov_b32 m0, s40
	s_waitcnt lgkmcnt(5)
	v_mfma_f32_32x32x16_bf16 v[114:129], v[182:185], v[146:149], v[98:113]
	ds_read_b128 v[182:185], v221 offset:4096
	v_exp_f32_e32 v66, v66
	v_exp_f32_e32 v67, v67
	v_exp_f32_e32 v68, v68
	s_waitcnt lgkmcnt(5)
	v_mfma_f32_32x32x16_bf16 v[114:129], v[222:225], v[150:153], v[114:129]
	ds_read_b128 v[222:225], v1 offset:4096
	v_exp_f32_e32 v69, v69
	v_add_f32_e32 v252, 0, v66
	v_exp_f32_e32 v70, v70
	s_add_i32 s75, s76, 2
	s_min_u32 s40, s75, 0x43
	s_lshl_b32 s40, s40, 17
	s_add_u32 s40, s50, s40
	s_addc_u32 s41, s51, 0
	s_lshl_b32 s79, s69, 14
	s_add_i32 s77, s72, s79
	v_lshl_add_u64 v[232:233], s[40:41], 0, v[194:195]
	s_mov_b32 vcc_lo, m0
	s_mov_b32 m0, s77
	s_nop 0
	global_load_lds_dwordx4 v[232:233], off
	s_mov_b32 m0, vcc_lo
	s_waitcnt lgkmcnt(5)
	v_mfma_f32_32x32x16_bf16 v[114:129], v[228:231], v[154:157], v[114:129]
	ds_read_b64_tr_b16 v[228:229], v226
	ds_read_b64_tr_b16 v[230:231], v226 offset:2048
	v_add_f32_e32 v252, v67, v252
	v_exp_f32_e32 v71, v71
	v_add_f32_e32 v252, v68, v252
	s_waitcnt lgkmcnt(6)
	v_mfma_f32_32x32x16_bf16 v[114:129], v[240:243], v[158:161], v[114:129]
	ds_read_b64_tr_b16 v[240:241], v207
	ds_read_b64_tr_b16 v[242:243], v207 offset:2048
	v_exp_f32_e32 v72, v72
	v_add_f32_e32 v252, v69, v252
	v_exp_f32_e32 v73, v73
	s_add_i32 s77, s73, s79
	v_lshl_add_u64 v[232:233], s[40:41], 0, v[196:197]
	s_mov_b32 s40, m0
	s_mov_b32 m0, s77
	s_nop 0
	global_load_lds_dwordx4 v[232:233], off
	s_mov_b32 m0, s40
	s_waitcnt lgkmcnt(7)
	v_mfma_f32_32x32x16_bf16 v[130:145], v[244:247], v[146:149], v[98:113]
	ds_read_b64_tr_b16 v[244:245], v235
	ds_read_b64_tr_b16 v[246:247], v235 offset:2048
	v_add_f32_e32 v252, v70, v252
	v_exp_f32_e32 v74, v74
	v_add_f32_e32 v252, v71, v252
	s_waitcnt lgkmcnt(8)
	v_mfma_f32_32x32x16_bf16 v[130:145], v[248:251], v[150:153], v[130:145]
	ds_read_b64_tr_b16 v[248:249], v227
	ds_read_b64_tr_b16 v[250:251], v227 offset:2048
	v_exp_f32_e32 v75, v75
	v_add_f32_e32 v252, v72, v252
	v_exp_f32_e32 v76, v76
	s_waitcnt lgkmcnt(9)
	v_mfma_f32_32x32x16_bf16 v[130:145], v[182:185], v[154:157], v[130:145]
	ds_read_b64_tr_b16 v[182:183], v226 offset:4096
	ds_read_b64_tr_b16 v[184:185], v226 offset:6144
	v_add_f32_e32 v252, v73, v252
	v_exp_f32_e32 v77, v77
	v_add_f32_e32 v252, v74, v252
	s_waitcnt lgkmcnt(10)
	v_mfma_f32_32x32x16_bf16 v[130:145], v[222:225], v[158:161], v[130:145]
	ds_read_b64_tr_b16 v[222:223], v207 offset:4096
	ds_read_b64_tr_b16 v[224:225], v207 offset:6144
	v_exp_f32_e32 v78, v78
	v_add_f32_e32 v252, v75, v252
	v_exp_f32_e32 v79, v79
	s_waitcnt lgkmcnt(10)
; #define LAS __attribute__((address_space(3)))
; #define MFMA32(a, b, c) __builtin_amdgcn_mfma_f32_32x32x16_bf16((a), (b), (c), 0, 0, 0)
; DI void attn_unit(const bf16_t* Q, const bf16_t* Kp, const bf16_t* Vp, bf16_t* O, size_t qrow0, size_t krow0, int ntile, int h, float lam, float lam_init, const float* gsub, LAS unsigned char* lds) {
;     ...
; #pragma unroll
;         for (int j = 0; j < 4; ++j) {
;             s16x4 lo[4], hi[4];
; #pragma unroll
;             for (int e = 0; e < 4; ++e) { LAS unsigned char* vp = vb + j * 4096 + ((e ^ q4) * 64);
;                 lo[e] = __builtin_bit_cast(s16x4, __builtin_amdgcn_ds_read_tr16_b64_v4i16((LAS s16x4*)vp));
;                 hi[e] = __builtin_bit_cast(s16x4, __builtin_amdgcn_ds_read_tr16_b64_v4i16((LAS s16x4*)(vp + 2048))); }
; #pragma unroll
;             for (int e = 0; e < 4; ++e) ot[e] = MFMA32(__builtin_shufflevector(lo[e], hi[e], 0, 1, 2, 3, 4, 5, 6, 7), __builtin_bit_cast(bf16x8, pp[j]), ot[e]);
;             __builtin_amdgcn_sched_barrier(0);
;         }
;         __builtin_amdgcn_s_setprio(0);
;         if (!shifted) {
;             ps = 0.f;
; #pragma unroll
;             for (int kh = 0; kh < 2; ++kh)
; #pragma unroll
;                 for (int i = 0; i < 16; ++i) { sc[kh][i] = __builtin_amdgcn_exp2f(sc[kh][i]); ps += sc[kh][i]; }
;             l_run += ps;
;         }
	v_mfma_f32_32x32x16_bf16 v[50:65], v[228:231], v[174:177], v[50:65]
	ds_read_b64_tr_b16 v[228:229], v235 offset:4096
	ds_read_b64_tr_b16 v[230:231], v235 offset:6144
	v_add_f32_e32 v252, v76, v252
	v_exp_f32_e32 v80, v80
	v_add_f32_e32 v252, v77, v252
	s_waitcnt lgkmcnt(10)
	v_mfma_f32_32x32x16_bf16 v[34:49], v[240:243], v[174:177], v[34:49]
	ds_read_b64_tr_b16 v[240:241], v227 offset:4096
	ds_read_b64_tr_b16 v[242:243], v227 offset:6144
	v_exp_f32_e32 v81, v81
	v_add_f32_e32 v252, v78, v252
	v_exp_f32_e32 v82, v82
	s_waitcnt lgkmcnt(10)
	v_mfma_f32_32x32x16_bf16 v[18:33], v[244:247], v[174:177], v[18:33]
	ds_read_b64_tr_b16 v[244:245], v226 offset:8192
	ds_read_b64_tr_b16 v[246:247], v226 offset:10240
	v_add_f32_e32 v252, v79, v252
	v_exp_f32_e32 v83, v83
	v_add_f32_e32 v252, v80, v252
	s_waitcnt lgkmcnt(10)
	v_mfma_f32_32x32x16_bf16 v[2:17], v[248:251], v[174:177], v[2:17]
	ds_read_b64_tr_b16 v[248:249], v207 offset:8192
	ds_read_b64_tr_b16 v[250:251], v207 offset:10240
	v_exp_f32_e32 v84, v84
	v_add_f32_e32 v252, v81, v252
	v_exp_f32_e32 v85, v85
	s_waitcnt lgkmcnt(10)
	v_mfma_f32_32x32x16_bf16 v[50:65], v[182:185], v[170:173], v[50:65]
	ds_read_b64_tr_b16 v[182:183], v235 offset:8192
	ds_read_b64_tr_b16 v[184:185], v235 offset:10240
	v_add_f32_e32 v252, v82, v252
	v_exp_f32_e32 v86, v86
	v_add_f32_e32 v252, v83, v252
	s_waitcnt lgkmcnt(10)
	v_mfma_f32_32x32x16_bf16 v[34:49], v[222:225], v[170:173], v[34:49]
	ds_read_b64_tr_b16 v[222:223], v227 offset:8192
	ds_read_b64_tr_b16 v[224:225], v227 offset:10240
	v_exp_f32_e32 v87, v87
	v_add_f32_e32 v252, v84, v252
	v_exp_f32_e32 v88, v88
	s_waitcnt lgkmcnt(10)
	v_mfma_f32_32x32x16_bf16 v[18:33], v[228:231], v[170:173], v[18:33]
	ds_read_b64_tr_b16 v[228:229], v226 offset:12288
	ds_read_b64_tr_b16 v[230:231], v226 offset:14336
	v_add_f32_e32 v252, v85, v252
	v_exp_f32_e32 v89, v89
	v_add_f32_e32 v252, v86, v252
	s_waitcnt lgkmcnt(10)
	v_mfma_f32_32x32x16_bf16 v[2:17], v[240:243], v[170:173], v[2:17]
	ds_read_b64_tr_b16 v[240:241], v207 offset:12288
	ds_read_b64_tr_b16 v[242:243], v207 offset:14336
	v_exp_f32_e32 v90, v90
	v_add_f32_e32 v252, v87, v252
	v_exp_f32_e32 v91, v91
	s_waitcnt lgkmcnt(10)
	v_mfma_f32_32x32x16_bf16 v[50:65], v[244:247], v[166:169], v[50:65]
	ds_read_b64_tr_b16 v[244:245], v235 offset:12288
	ds_read_b64_tr_b16 v[246:247], v235 offset:14336
	v_add_f32_e32 v252, v88, v252
	v_exp_f32_e32 v92, v92
	v_add_f32_e32 v252, v89, v252
	s_waitcnt lgkmcnt(10)
	v_mfma_f32_32x32x16_bf16 v[34:49], v[248:251], v[166:169], v[34:49]
	ds_read_b64_tr_b16 v[248:249], v227 offset:12288
	ds_read_b64_tr_b16 v[250:251], v227 offset:14336
	v_exp_f32_e32 v93, v93
	v_add_f32_e32 v252, v90, v252
	v_exp_f32_e32 v94, v94
	s_waitcnt lgkmcnt(10)
	v_mfma_f32_32x32x16_bf16 v[18:33], v[182:185], v[166:169], v[18:33]
	v_add_f32_e32 v252, v91, v252
	v_exp_f32_e32 v95, v95
	v_add_f32_e32 v252, v92, v252
	s_waitcnt lgkmcnt(8)
	v_mfma_f32_32x32x16_bf16 v[2:17], v[222:225], v[166:169], v[2:17]
	v_exp_f32_e32 v96, v96
	v_add_f32_e32 v252, v93, v252
	v_exp_f32_e32 v97, v97
	s_waitcnt lgkmcnt(6)
	v_mfma_f32_32x32x16_bf16 v[50:65], v[228:231], v[162:165], v[50:65]
	v_add_f32_e32 v252, v94, v252
	v_add_f32_e32 v252, v95, v252
	v_add_f32_e32 v252, v96, v252
	s_waitcnt lgkmcnt(4)
	v_mfma_f32_32x32x16_bf16 v[34:49], v[240:243], v[162:165], v[34:49]
	v_add_f32_e32 v220, v97, v252
	v_add_f32_e32 v213, v213, v220
	s_waitcnt lgkmcnt(2)
	v_mfma_f32_32x32x16_bf16 v[18:33], v[244:247], v[162:165], v[18:33]
	s_waitcnt lgkmcnt(0)
	v_mfma_f32_32x32x16_bf16 v[2:17], v[248:251], v[162:165], v[2:17]
	s_setprio 0
	v_cndmask_b32_e64 v1, 0, 1, s[54:55]
	v_cmp_ne_u32_e64 s[40:41], 1, v1
	s_andn2_b64 vcc, exec, s[54:55]
	s_cbranch_vccnz .LBB0_575

; DI void attn_unit(const bf16_t* Q, const bf16_t* Kp, const bf16_t* Vp, bf16_t* O, size_t qrow0, size_t krow0, int ntile, int h, float lam, float lam_init, const float* gsub, LAS unsigned char* lds) {
;     ...
;             for (int s2 = 0; s2 < 2; ++s2) { u32x4 pa; pa.x = cvtpk(sc[kh][8 * s2], sc[kh][8 * s2 + 1]); pa.y = cvtpk(sc[kh][8 * s2 + 2], sc[kh][8 * s2 + 3]); pa.z = cvtpk(sc[kh][8 * s2 + 4], sc[kh][8 * s2 + 5]); pa.w = cvtpk(sc[kh][8 * s2 + 6], sc[kh][8 * s2 + 7]);
;     ...
;         { const int tk = (t1 + 4 < ntile) ? t1 + 4 : ntile - 1; AT_ISSUE_K(tk, ks0); const int tv = (t1 + 2 < ntile) ? t1 + 2 : ntile - 1; AT_ISSUE_V(tv, vs1); }
;         LAS unsigned char* kb = lds + KRING + ks1 * SLOT + kro;
;         LAS unsigned char* vb = lds + VRING + vsm1 * SLOT + vro;
;         __builtin_amdgcn_s_setprio(1);
;         { bf16x8 ql[4];
; #pragma unroll
;           for (int d0 = 0; d0 < 4; ++d0) ql[d0] = qf[d0];
; #pragma unroll
;           for (int kh = 0; kh < 2; ++kh) {
;             bf16x8 kf[4];
; #pragma unroll
;             for (int e = 0; e < 4; ++e) kf[e] = *(const LAS bf16x8*)(kb + kh * 4096 + (((2 * e + hh) ^ ksw) * 16));
;             sc[kh] = MFMA32(kf[0], ql[0], negm);
; #pragma unroll
;             for (int d0 = 1; d0 < 4; ++d0) sc[kh] = MFMA32(kf[d0], ql[d0], sc[kh]);
;             __builtin_amdgcn_sched_barrier(0);
;           } }
; #pragma unroll
;         for (int j = 0; j < 4; ++j) {
;             s16x4 lo[4], hi[4];
; #pragma unroll
;             for (int e = 0; e < 4; ++e) { LAS unsigned char* vp = vb + j * 4096 + ((e ^ q4) * 64);
;                 lo[e] = __builtin_bit_cast(s16x4, __builtin_amdgcn_ds_read_tr16_b64_v4i16((LAS s16x4*)vp));
;                 hi[e] = __builtin_bit_cast(s16x4, __builtin_amdgcn_ds_read_tr16_b64_v4i16((LAS s16x4*)(vp + 2048))); }
; #pragma unroll
;             for (int e = 0; e < 4; ++e) ot[e] = MFMA32(__builtin_shufflevector(lo[e], hi[e], 0, 1, 2, 3, 4, 5, 6, 7), __builtin_bit_cast(bf16x8, pp[j]), ot[e]);
;             __builtin_amdgcn_sched_barrier(0);
;         }
;         __builtin_amdgcn_s_setprio(0);
;         if (!shifted) {
;             ps = 0.f;
; #pragma unroll
;             for (int kh = 0; kh < 2; ++kh)
; #pragma unroll
;                 for (int i = 0; i < 16; ++i) { sn[kh][i] = __builtin_amdgcn_exp2f(sn[kh][i]); ps += sn[kh][i]; }
;             l_run += ps;
;         }
.LBB0_579:
	s_min_u32 s81, s76, 62
	s_lshl_b32 s92, s81, 17
	s_add_i32 s77, s74, 1
	s_and_b32 s77, s77, 3
	s_addk_i32 s78, 0x4000
	s_and_b32 s78, s78, 0xc000
	s_setprio 1
	v_lshl_add_u32 v1, s77, 14, v200
	v_add_u32_e32 v226, v1, v201
	v_add_u32_e32 v207, v1, v202
	v_add_u32_e32 v221, v1, v203
	v_add_u32_e32 v1, v1, v204
	ds_read_b128 v[182:185], v226
	ds_read_b128 v[222:225], v207
	ds_read_b128 v[228:231], v221
	ds_read_b128 v[240:243], v1
	ds_read_b128 v[244:247], v226 offset:4096
	ds_read_b128 v[248:251], v207 offset:4096
	v_add_u32_e32 v227, s78, v219
	v_add_u32_e32 v226, v227, v218
	v_add_u32_e32 v207, v227, v217
	v_add_u32_e32 v235, v227, v216
	v_add_u32_e32 v227, v227, v214
	v_cvt_pk_bf16_f32 v170, v66, v67
	v_cvt_pk_bf16_f32 v171, v68, v69
	v_cvt_pk_bf16_f32 v172, v70, v71
	v_cvt_pk_bf16_f32 v173, v72, v73
	v_cvt_pk_bf16_f32 v174, v74, v75
	v_cvt_pk_bf16_f32 v175, v76, v77
	v_cvt_pk_bf16_f32 v176, v78, v79
	v_cvt_pk_bf16_f32 v177, v80, v81
	v_cvt_pk_bf16_f32 v166, v82, v83
	v_cvt_pk_bf16_f32 v167, v84, v85
	v_cvt_pk_bf16_f32 v168, v86, v87
	v_cvt_pk_bf16_f32 v169, v88, v89
	v_cvt_pk_bf16_f32 v162, v90, v91
	v_cvt_pk_bf16_f32 v163, v92, v93
	v_cvt_pk_bf16_f32 v164, v94, v95
	v_cvt_pk_bf16_f32 v165, v96, v97
	v_lshl_add_u64 v[232:233], v[198:199], 0, s[92:93]
	s_mov_b64 s[82:83], 0xa0000
	v_lshl_add_u64 v[232:233], v[232:233], 0, s[82:83]
	s_add_i32 s81, s80, s68
	s_mov_b32 s82, m0
	s_mov_b32 m0, s81
	s_nop 0
	global_load_lds_dwordx4 v[232:233], off
	s_mov_b32 m0, s82
	s_waitcnt lgkmcnt(5)
	v_mfma_f32_32x32x16_bf16 v[66:81], v[182:185], v[146:149], v[98:113]
	ds_read_b128 v[182:185], v221 offset:4096
	v_exp_f32_e32 v114, v114
	v_exp_f32_e32 v115, v115
	v_exp_f32_e32 v116, v116
	s_waitcnt lgkmcnt(5)
	v_mfma_f32_32x32x16_bf16 v[66:81], v[222:225], v[150:153], v[66:81]
	ds_read_b128 v[222:225], v1 offset:4096
	v_exp_f32_e32 v117, v117
	v_add_f32_e32 v252, 0, v114
	v_exp_f32_e32 v118, v118
	s_add_i32 s82, s80, s71
	s_mov_b64 s[80:81], 0x80
	v_lshl_add_u64 v[232:233], v[232:233], 0, s[80:81]
	s_mov_b32 s80, m0
	s_mov_b32 m0, s82
	s_nop 0
	global_load_lds_dwordx4 v[232:233], off
	s_mov_b32 m0, s80
	s_waitcnt lgkmcnt(5)
	v_mfma_f32_32x32x16_bf16 v[66:81], v[228:231], v[154:157], v[66:81]
	ds_read_b64_tr_b16 v[228:229], v226
	ds_read_b64_tr_b16 v[230:231], v226 offset:2048
	v_add_f32_e32 v252, v115, v252
	v_exp_f32_e32 v119, v119
	v_add_f32_e32 v252, v116, v252
	s_waitcnt lgkmcnt(6)
	v_mfma_f32_32x32x16_bf16 v[66:81], v[240:243], v[158:161], v[66:81]
	ds_read_b64_tr_b16 v[240:241], v207
	ds_read_b64_tr_b16 v[242:243], v207 offset:2048
	v_exp_f32_e32 v120, v120
	v_add_f32_e32 v252, v117, v252
	v_exp_f32_e32 v121, v121
	s_min_u32 s80, s76, 64
	s_lshl_b32 s80, s80, 17
	s_add_u32 s80, s50, s80
	s_addc_u32 s81, s51, 0
	s_add_u32 s80, s80, 0x60000
	s_addc_u32 s81, s81, 0
	s_addk_i32 s79, 0x4000
	s_or_b32 s82, s79, 0x10000
	s_add_i32 s82, s82, s68
	s_or_b32 s79, s79, 0x12000
	v_lshl_add_u64 v[232:233], s[80:81], 0, v[194:195]
	s_mov_b32 s83, m0
	s_mov_b32 m0, s82
	s_nop 0
	global_load_lds_dwordx4 v[232:233], off
	s_mov_b32 m0, s83
	s_waitcnt lgkmcnt(7)
	v_mfma_f32_32x32x16_bf16 v[82:97], v[244:247], v[146:149], v[98:113]
	ds_read_b64_tr_b16 v[244:245], v235
	ds_read_b64_tr_b16 v[246:247], v235 offset:2048
	v_add_f32_e32 v252, v118, v252
	v_exp_f32_e32 v122, v122
	v_add_f32_e32 v252, v119, v252
	s_waitcnt lgkmcnt(8)
	v_mfma_f32_32x32x16_bf16 v[82:97], v[248:251], v[150:153], v[82:97]
	ds_read_b64_tr_b16 v[248:249], v227
	ds_read_b64_tr_b16 v[250:251], v227 offset:2048
	v_exp_f32_e32 v123, v123
	v_add_f32_e32 v252, v120, v252
	v_exp_f32_e32 v124, v124
	s_add_i32 s79, s79, s68
	v_lshl_add_u64 v[232:233], s[80:81], 0, v[196:197]
	s_mov_b32 s80, m0
	s_mov_b32 m0, s79
	s_nop 0
	global_load_lds_dwordx4 v[232:233], off
	s_mov_b32 m0, s80
	s_waitcnt lgkmcnt(9)
	v_mfma_f32_32x32x16_bf16 v[82:97], v[182:185], v[154:157], v[82:97]
	ds_read_b64_tr_b16 v[182:183], v226 offset:4096
	ds_read_b64_tr_b16 v[184:185], v226 offset:6144
	v_add_f32_e32 v252, v121, v252
	v_exp_f32_e32 v125, v125
	v_add_f32_e32 v252, v122, v252
	s_waitcnt lgkmcnt(10)
; #define LAS __attribute__((address_space(3)))
; #define MFMA32(a, b, c) __builtin_amdgcn_mfma_f32_32x32x16_bf16((a), (b), (c), 0, 0, 0)
; DI void attn_unit(const bf16_t* Q, const bf16_t* Kp, const bf16_t* Vp, bf16_t* O, size_t qrow0, size_t krow0, int ntile, int h, float lam, float lam_init, const float* gsub, LAS unsigned char* lds) {
;     ...
; #pragma unroll
;         for (int j = 0; j < 4; ++j) {
;             s16x4 lo[4], hi[4];
; #pragma unroll
;             for (int e = 0; e < 4; ++e) { LAS unsigned char* vp = vb + j * 4096 + ((e ^ q4) * 64);
;                 lo[e] = __builtin_bit_cast(s16x4, __builtin_amdgcn_ds_read_tr16_b64_v4i16((LAS s16x4*)vp));
;                 hi[e] = __builtin_bit_cast(s16x4, __builtin_amdgcn_ds_read_tr16_b64_v4i16((LAS s16x4*)(vp + 2048))); }
; #pragma unroll
;             for (int e = 0; e < 4; ++e) ot[e] = MFMA32(__builtin_shufflevector(lo[e], hi[e], 0, 1, 2, 3, 4, 5, 6, 7), __builtin_bit_cast(bf16x8, pp[j]), ot[e]);
;             __builtin_amdgcn_sched_barrier(0);
;         }
;         __builtin_amdgcn_s_setprio(0);
;         if (!shifted) {
;             ps = 0.f;
; #pragma unroll
;             for (int kh = 0; kh < 2; ++kh)
; #pragma unroll
;                 for (int i = 0; i < 16; ++i) { sn[kh][i] = __builtin_amdgcn_exp2f(sn[kh][i]); ps += sn[kh][i]; }
;             l_run += ps;
;         }
	v_mfma_f32_32x32x16_bf16 v[82:97], v[222:225], v[158:161], v[82:97]
	ds_read_b64_tr_b16 v[222:223], v207 offset:4096
	ds_read_b64_tr_b16 v[224:225], v207 offset:6144
	v_exp_f32_e32 v126, v126
	v_add_f32_e32 v252, v123, v252
	v_exp_f32_e32 v127, v127
	s_waitcnt lgkmcnt(10)
	v_mfma_f32_32x32x16_bf16 v[50:65], v[228:231], v[170:173], v[50:65]
	ds_read_b64_tr_b16 v[228:229], v235 offset:4096
	ds_read_b64_tr_b16 v[230:231], v235 offset:6144
	v_add_f32_e32 v252, v124, v252
	v_exp_f32_e32 v128, v128
	v_add_f32_e32 v252, v125, v252
	s_waitcnt lgkmcnt(10)
	v_mfma_f32_32x32x16_bf16 v[34:49], v[240:243], v[170:173], v[34:49]
	ds_read_b64_tr_b16 v[240:241], v227 offset:4096
	ds_read_b64_tr_b16 v[242:243], v227 offset:6144
	v_exp_f32_e32 v129, v129
	v_add_f32_e32 v252, v126, v252
	v_exp_f32_e32 v130, v130
	s_waitcnt lgkmcnt(10)
	v_mfma_f32_32x32x16_bf16 v[18:33], v[244:247], v[170:173], v[18:33]
	ds_read_b64_tr_b16 v[244:245], v226 offset:8192
	ds_read_b64_tr_b16 v[246:247], v226 offset:10240
	v_add_f32_e32 v252, v127, v252
	v_exp_f32_e32 v131, v131
	v_add_f32_e32 v252, v128, v252
	s_waitcnt lgkmcnt(10)
	v_mfma_f32_32x32x16_bf16 v[2:17], v[248:251], v[170:173], v[2:17]
	ds_read_b64_tr_b16 v[248:249], v207 offset:8192
	ds_read_b64_tr_b16 v[250:251], v207 offset:10240
	v_exp_f32_e32 v132, v132
	v_add_f32_e32 v252, v129, v252
	v_exp_f32_e32 v133, v133
	s_waitcnt lgkmcnt(10)
	v_mfma_f32_32x32x16_bf16 v[50:65], v[182:185], v[174:177], v[50:65]
	ds_read_b64_tr_b16 v[182:183], v235 offset:8192
	ds_read_b64_tr_b16 v[184:185], v235 offset:10240
	v_add_f32_e32 v252, v130, v252
	v_exp_f32_e32 v134, v134
	v_add_f32_e32 v252, v131, v252
	s_waitcnt lgkmcnt(10)
	v_mfma_f32_32x32x16_bf16 v[34:49], v[222:225], v[174:177], v[34:49]
	ds_read_b64_tr_b16 v[222:223], v227 offset:8192
	ds_read_b64_tr_b16 v[224:225], v227 offset:10240
	v_exp_f32_e32 v135, v135
	v_add_f32_e32 v252, v132, v252
	v_exp_f32_e32 v136, v136
	s_waitcnt lgkmcnt(10)
	v_mfma_f32_32x32x16_bf16 v[18:33], v[228:231], v[174:177], v[18:33]
	ds_read_b64_tr_b16 v[228:229], v226 offset:12288
	ds_read_b64_tr_b16 v[230:231], v226 offset:14336
	v_add_f32_e32 v252, v133, v252
	v_exp_f32_e32 v137, v137
	v_add_f32_e32 v252, v134, v252
	s_waitcnt lgkmcnt(10)
	v_mfma_f32_32x32x16_bf16 v[2:17], v[240:243], v[174:177], v[2:17]
	ds_read_b64_tr_b16 v[240:241], v207 offset:12288
	ds_read_b64_tr_b16 v[242:243], v207 offset:14336
	v_exp_f32_e32 v138, v138
	v_add_f32_e32 v252, v135, v252
	v_exp_f32_e32 v139, v139
	s_waitcnt lgkmcnt(10)
	v_mfma_f32_32x32x16_bf16 v[50:65], v[244:247], v[166:169], v[50:65]
	ds_read_b64_tr_b16 v[244:245], v235 offset:12288
	ds_read_b64_tr_b16 v[246:247], v235 offset:14336
	v_add_f32_e32 v252, v136, v252
	v_exp_f32_e32 v140, v140
	v_add_f32_e32 v252, v137, v252
	s_waitcnt lgkmcnt(10)
	v_mfma_f32_32x32x16_bf16 v[34:49], v[248:251], v[166:169], v[34:49]
	ds_read_b64_tr_b16 v[248:249], v227 offset:12288
	ds_read_b64_tr_b16 v[250:251], v227 offset:14336
	v_exp_f32_e32 v141, v141
	v_add_f32_e32 v252, v138, v252
	v_exp_f32_e32 v142, v142
	s_waitcnt lgkmcnt(10)
	v_mfma_f32_32x32x16_bf16 v[18:33], v[182:185], v[166:169], v[18:33]
	v_add_f32_e32 v252, v139, v252
	v_exp_f32_e32 v143, v143
	v_add_f32_e32 v252, v140, v252
	s_waitcnt lgkmcnt(8)
	v_mfma_f32_32x32x16_bf16 v[2:17], v[222:225], v[166:169], v[2:17]
	v_exp_f32_e32 v144, v144
	v_add_f32_e32 v252, v141, v252
	v_exp_f32_e32 v145, v145
	s_waitcnt lgkmcnt(6)
	v_mfma_f32_32x32x16_bf16 v[50:65], v[228:231], v[162:165], v[50:65]
	v_add_f32_e32 v252, v142, v252
	v_add_f32_e32 v252, v143, v252
	v_add_f32_e32 v252, v144, v252
	s_waitcnt lgkmcnt(4)
	v_mfma_f32_32x32x16_bf16 v[34:49], v[240:243], v[162:165], v[34:49]
	v_add_f32_e32 v220, v145, v252
	v_add_f32_e32 v213, v213, v220
	s_waitcnt lgkmcnt(2)
	v_mfma_f32_32x32x16_bf16 v[18:33], v[244:247], v[162:165], v[18:33]
	s_waitcnt lgkmcnt(0)
	v_mfma_f32_32x32x16_bf16 v[2:17], v[248:251], v[162:165], v[2:17]
	s_setprio 0
	s_and_b64 vcc, exec, s[40:41]
	s_cbranch_vccnz .LBB0_581
